# grid barriers 2-10 hand-written with static generation (arrival atomic first, no integer divisions, compact poll), padded so later code keeps its 64-byte alignment
# speedup vs baseline: 1.0140x; 1.0011x over previous
.LBB0_284:
	s_and_b64 vcc, exec, s[0:1]
	s_cbranch_vccz .LBB0_338
	v_cmp_eq_u32_e32 vcc, 0, v102
	s_and_saveexec_b64 s[0:1], vcc
	s_cbranch_execz .LBB0_337
	s_getreg_b32 s3, hwreg(HW_REG_XCC_ID, 0, 4)
	s_lshl_b32 s3, s3, 8
	s_add_u32 s4, s74, 0x5400
	s_addc_u32 s5, s75, 0
	s_add_u32 s4, s4, s3
	s_addc_u32 s5, s5, 0
	v_mov_b32_e32 v3, 0
	v_mov_b32_e32 v4, 1
	s_waitcnt vmcnt(0) expcnt(0) lgkmcnt(0)
	global_atomic_add v3, v3, v4, s[4:5] sc0
	v_mov_b32_e32 v0, 0x20160
	ds_read_b32 v2, v0
	ds_read_b32 v0, v0 offset:4
	s_waitcnt vmcnt(0) lgkmcnt(0)
	v_mul_u32_u24_e32 v1, 2, v2
	v_add_u32_e32 v3, 1, v3
	v_cmp_ne_u32_e32 vcc, v3, v1
	s_cbranch_vccnz .Lxb_poll_2
	buffer_wbl2 sc1
	v_mov_b32_e32 v3, 0x7400
	s_waitcnt vmcnt(0)
	global_atomic_add v3, v3, v4, s[74:75] sc0
	v_mul_u32_u24_e32 v1, 2, v0
	s_waitcnt vmcnt(0)
	v_add_u32_e32 v3, 1, v3
	v_cmp_ne_u32_e32 vcc, v3, v1
	s_cbranch_vccnz .Lxb_poll_2
	v_mov_b32_e32 v3, 0x7500
	global_atomic_add v3, v4, s[74:75]
	buffer_inv sc1
	s_branch .Lxb_done_2
.Lxb_poll_2:
	buffer_inv sc1
	v_mov_b32_e32 v3, 0x7500
	s_mov_b32 s3, 0x80000
.Lxb_loop_2:
	global_load_dword v1, v3, s[74:75] sc1
	s_waitcnt vmcnt(0)
	v_cmp_gt_u32_e32 vcc, 2, v1
	s_cbranch_vccz .Lxb_done_2
	s_sleep 1
	s_add_u32 s3, s3, -1
	s_cmp_lg_u32 s3, 0
	s_cbranch_scc1 .Lxb_loop_2
.Lxb_done_2:
	s_waitcnt vmcnt(0)
	s_nop 0
	s_nop 0
	s_nop 0
	s_nop 0
	s_nop 0
	s_nop 0
	s_nop 0
	s_nop 0
	s_nop 0
	s_nop 0
	s_nop 0
	s_nop 0
	s_nop 0
	s_nop 0
	s_nop 0

.LBB0_449:
	s_and_b64 vcc, exec, s[0:1]
	s_cbranch_vccz .LBB0_503
	v_cmp_eq_u32_e32 vcc, 0, v102
	s_and_saveexec_b64 s[0:1], vcc
	s_cbranch_execz .LBB0_502
	s_getreg_b32 s3, hwreg(HW_REG_XCC_ID, 0, 4)
	s_lshl_b32 s3, s3, 8
	s_add_u32 s4, s74, 0x5400
	s_addc_u32 s5, s75, 0
	s_add_u32 s4, s4, s3
	s_addc_u32 s5, s5, 0
	v_mov_b32_e32 v3, 0
	v_mov_b32_e32 v4, 1
	s_waitcnt vmcnt(0) expcnt(0) lgkmcnt(0)
	global_atomic_add v3, v3, v4, s[4:5] sc0
	v_mov_b32_e32 v0, 0x20160
	ds_read_b32 v2, v0
	ds_read_b32 v0, v0 offset:4
	s_waitcnt vmcnt(0) lgkmcnt(0)
	v_mul_u32_u24_e32 v1, 3, v2
	v_add_u32_e32 v3, 1, v3
	v_cmp_ne_u32_e32 vcc, v3, v1
	s_cbranch_vccnz .Lxb_poll_3
	buffer_wbl2 sc1
	v_mov_b32_e32 v3, 0x7400
	s_waitcnt vmcnt(0)
	global_atomic_add v3, v3, v4, s[74:75] sc0
	v_mul_u32_u24_e32 v1, 3, v0
	s_waitcnt vmcnt(0)
	v_add_u32_e32 v3, 1, v3
	v_cmp_ne_u32_e32 vcc, v3, v1
	s_cbranch_vccnz .Lxb_poll_3
	v_mov_b32_e32 v3, 0x7500
	global_atomic_add v3, v4, s[74:75]
	buffer_inv sc1
	s_branch .Lxb_done_3

.Lxb_loop_3:
	global_load_dword v1, v3, s[74:75] sc1
	s_waitcnt vmcnt(0)
	v_cmp_gt_u32_e32 vcc, 3, v1
	s_cbranch_vccz .Lxb_done_3
	s_sleep 1
	s_add_u32 s3, s3, -1
	s_cmp_lg_u32 s3, 0
	s_cbranch_scc1 .Lxb_loop_3

.LBB0_623:
	s_and_b64 vcc, exec, s[0:1]
	s_cbranch_vccz .LBB0_677
	v_cmp_eq_u32_e32 vcc, 0, v102
	s_and_saveexec_b64 s[0:1], vcc
	s_cbranch_execz .LBB0_676
	s_getreg_b32 s3, hwreg(HW_REG_XCC_ID, 0, 4)
	s_lshl_b32 s3, s3, 8
	s_add_u32 s4, s74, 0x5400
	s_addc_u32 s5, s75, 0
	s_add_u32 s4, s4, s3
	s_addc_u32 s5, s5, 0
	v_mov_b32_e32 v3, 0
	v_mov_b32_e32 v4, 1
	s_waitcnt vmcnt(0) expcnt(0) lgkmcnt(0)
	global_atomic_add v3, v3, v4, s[4:5] sc0
	v_mov_b32_e32 v0, 0x20160
	ds_read_b32 v2, v0
	ds_read_b32 v0, v0 offset:4
	s_waitcnt vmcnt(0) lgkmcnt(0)
	v_mul_u32_u24_e32 v1, 4, v2
	v_add_u32_e32 v3, 1, v3
	v_cmp_ne_u32_e32 vcc, v3, v1
	s_cbranch_vccnz .Lxb_poll_4
	buffer_wbl2 sc1
	v_mov_b32_e32 v3, 0x7400
	s_waitcnt vmcnt(0)
	global_atomic_add v3, v3, v4, s[74:75] sc0
	v_mul_u32_u24_e32 v1, 4, v0
	s_waitcnt vmcnt(0)
	v_add_u32_e32 v3, 1, v3
	v_cmp_ne_u32_e32 vcc, v3, v1
	s_cbranch_vccnz .Lxb_poll_4
	v_mov_b32_e32 v3, 0x7500
	global_atomic_add v3, v4, s[74:75]
	buffer_inv sc1
	s_branch .Lxb_done_4

.Lxb_loop_4:
	global_load_dword v1, v3, s[74:75] sc1
	s_waitcnt vmcnt(0)
	v_cmp_gt_u32_e32 vcc, 4, v1
	s_cbranch_vccz .Lxb_done_4
	s_sleep 1
	s_add_u32 s3, s3, -1
	s_cmp_lg_u32 s3, 0
	s_cbranch_scc1 .Lxb_loop_4

.LBB0_779:
	s_and_b64 vcc, exec, s[0:1]
	s_cbranch_vccz .LBB0_833
	v_cmp_eq_u32_e32 vcc, 0, v102
	s_and_saveexec_b64 s[0:1], vcc
	s_cbranch_execz .LBB0_832
	s_getreg_b32 s3, hwreg(HW_REG_XCC_ID, 0, 4)
	s_lshl_b32 s3, s3, 8
	s_add_u32 s4, s74, 0x5400
	s_addc_u32 s5, s75, 0
	s_add_u32 s4, s4, s3
	s_addc_u32 s5, s5, 0
	v_mov_b32_e32 v3, 0
	v_mov_b32_e32 v4, 1
	s_waitcnt vmcnt(0) expcnt(0) lgkmcnt(0)
	global_atomic_add v3, v3, v4, s[4:5] sc0
	v_mov_b32_e32 v0, 0x20160
	ds_read_b32 v2, v0
	ds_read_b32 v0, v0 offset:4
	s_waitcnt vmcnt(0) lgkmcnt(0)
	v_mul_u32_u24_e32 v1, 5, v2
	v_add_u32_e32 v3, 1, v3
	v_cmp_ne_u32_e32 vcc, v3, v1
	s_cbranch_vccnz .Lxb_poll_5
	buffer_wbl2 sc1
	v_mov_b32_e32 v3, 0x7400
	s_waitcnt vmcnt(0)
	global_atomic_add v3, v3, v4, s[74:75] sc0
	v_mul_u32_u24_e32 v1, 5, v0
	s_waitcnt vmcnt(0)
	v_add_u32_e32 v3, 1, v3
	v_cmp_ne_u32_e32 vcc, v3, v1
	s_cbranch_vccnz .Lxb_poll_5
	v_mov_b32_e32 v3, 0x7500
	global_atomic_add v3, v4, s[74:75]
	buffer_inv sc1
	s_branch .Lxb_done_5

.Lxb_loop_5:
	global_load_dword v1, v3, s[74:75] sc1
	s_waitcnt vmcnt(0)
	v_cmp_gt_u32_e32 vcc, 5, v1
	s_cbranch_vccz .Lxb_done_5
	s_sleep 1
	s_add_u32 s3, s3, -1
	s_cmp_lg_u32 s3, 0
	s_cbranch_scc1 .Lxb_loop_5
.Lxb_done_5:
	s_waitcnt vmcnt(0)
.LBB0_832:
	s_or_b64 exec, exec, s[0:1]

.LBB0_953:
	v_readlane_b32 s66, v238, 3
	s_and_b64 vcc, exec, s[0:1]
	v_readlane_b32 s67, v238, 4
	s_cbranch_vccz .LBB0_1007
	v_cmp_eq_u32_e32 vcc, 0, v102
	s_and_saveexec_b64 s[0:1], vcc
	s_cbranch_execz .LBB0_1006
	s_getreg_b32 s3, hwreg(HW_REG_XCC_ID, 0, 4)
	s_lshl_b32 s3, s3, 8
	s_add_u32 s4, s74, 0x5400
	s_addc_u32 s5, s75, 0
	s_add_u32 s4, s4, s3
	s_addc_u32 s5, s5, 0
	v_mov_b32_e32 v3, 0
	v_mov_b32_e32 v4, 1
	s_waitcnt vmcnt(0) expcnt(0) lgkmcnt(0)
	global_atomic_add v3, v3, v4, s[4:5] sc0
	v_mov_b32_e32 v0, 0x20160
	ds_read_b32 v2, v0
	ds_read_b32 v0, v0 offset:4
	s_waitcnt vmcnt(0) lgkmcnt(0)
	v_mul_u32_u24_e32 v1, 6, v2
	v_add_u32_e32 v3, 1, v3
	v_cmp_ne_u32_e32 vcc, v3, v1
	s_cbranch_vccnz .Lxb_poll_6
	buffer_wbl2 sc1
	v_mov_b32_e32 v3, 0x7400
	s_waitcnt vmcnt(0)
	global_atomic_add v3, v3, v4, s[74:75] sc0
	v_mul_u32_u24_e32 v1, 6, v0
	s_waitcnt vmcnt(0)
	v_add_u32_e32 v3, 1, v3
	v_cmp_ne_u32_e32 vcc, v3, v1
	s_cbranch_vccnz .Lxb_poll_6
	v_mov_b32_e32 v3, 0x7500
	global_atomic_add v3, v4, s[74:75]
	buffer_inv sc1
	s_branch .Lxb_done_6

.Lxb_loop_6:
	global_load_dword v1, v3, s[74:75] sc1
	s_waitcnt vmcnt(0)
	v_cmp_gt_u32_e32 vcc, 6, v1
	s_cbranch_vccz .Lxb_done_6
	s_sleep 1
	s_add_u32 s3, s3, -1
	s_cmp_lg_u32 s3, 0
	s_cbranch_scc1 .Lxb_loop_6
.Lxb_done_6:
	s_waitcnt vmcnt(0)
	s_nop 0
	s_nop 0
	s_nop 0
	s_nop 0
	s_nop 0
	s_nop 0
	s_nop 0
	s_nop 0
	s_nop 0
	s_nop 0
	s_nop 0

.LBB0_1023:
	s_waitcnt vmcnt(0)
	s_barrier
	s_mov_b64 s[0:1], exec
	v_readlane_b32 s4, v238, 1
	v_readlane_b32 s5, v238, 2
	s_and_b64 s[4:5], s[0:1], s[4:5]
	s_mov_b64 exec, s[4:5]
	s_cbranch_execz .LBB0_1075
	s_getreg_b32 s3, hwreg(HW_REG_XCC_ID, 0, 4)
	s_lshl_b32 s3, s3, 8
	s_add_u32 s4, s74, 0x5400
	s_addc_u32 s5, s75, 0
	s_add_u32 s4, s4, s3
	s_addc_u32 s5, s5, 0
	v_mov_b32_e32 v3, 0
	v_mov_b32_e32 v4, 1
	s_waitcnt vmcnt(0) expcnt(0) lgkmcnt(0)
	global_atomic_add v3, v3, v4, s[4:5] sc0
	v_mov_b32_e32 v0, 0x20160
	ds_read_b32 v2, v0
	ds_read_b32 v0, v0 offset:4
	s_waitcnt vmcnt(0) lgkmcnt(0)
	v_mul_u32_u24_e32 v1, 7, v2
	v_add_u32_e32 v3, 1, v3
	v_cmp_ne_u32_e32 vcc, v3, v1
	s_cbranch_vccnz .Lxb_poll_7
	buffer_wbl2 sc1
	v_mov_b32_e32 v3, 0x7400
	s_waitcnt vmcnt(0)
	global_atomic_add v3, v3, v4, s[74:75] sc0
	v_mul_u32_u24_e32 v1, 7, v0
	s_waitcnt vmcnt(0)
	v_add_u32_e32 v3, 1, v3
	v_cmp_ne_u32_e32 vcc, v3, v1
	s_cbranch_vccnz .Lxb_poll_7
	v_mov_b32_e32 v3, 0x7500
	global_atomic_add v3, v4, s[74:75]
	buffer_inv sc1
	s_branch .Lxb_done_7

.Lxb_loop_7:
	global_load_dword v1, v3, s[74:75] sc1
	s_waitcnt vmcnt(0)
	v_cmp_gt_u32_e32 vcc, 7, v1
	s_cbranch_vccz .Lxb_done_7
	s_sleep 1
	s_add_u32 s3, s3, -1
	s_cmp_lg_u32 s3, 0
	s_cbranch_scc1 .Lxb_loop_7
.Lxb_done_7:
	s_waitcnt vmcnt(0)
	s_nop 0
	s_nop 0
	s_nop 0
	s_nop 0
	s_nop 0
	s_nop 0
	s_nop 0
	s_nop 0
	s_nop 0
	s_nop 0

.LBB0_1147:
	s_waitcnt vmcnt(0)
	s_barrier
	s_mov_b64 s[0:1], exec
	v_readlane_b32 s4, v238, 1
	v_readlane_b32 s5, v238, 2
	s_and_b64 s[4:5], s[0:1], s[4:5]
	s_mov_b64 exec, s[4:5]
	s_cbranch_execz .LBB0_1199
	s_getreg_b32 s3, hwreg(HW_REG_XCC_ID, 0, 4)
	s_lshl_b32 s3, s3, 8
	s_add_u32 s4, s74, 0x5400
	s_addc_u32 s5, s75, 0
	s_add_u32 s4, s4, s3
	s_addc_u32 s5, s5, 0
	v_mov_b32_e32 v3, 0
	v_mov_b32_e32 v4, 1
	s_waitcnt vmcnt(0) expcnt(0) lgkmcnt(0)
	global_atomic_add v3, v3, v4, s[4:5] sc0
	v_mov_b32_e32 v0, 0x20160
	ds_read_b32 v2, v0
	ds_read_b32 v0, v0 offset:4
	s_waitcnt vmcnt(0) lgkmcnt(0)
	v_mul_u32_u24_e32 v1, 8, v2
	v_add_u32_e32 v3, 1, v3
	v_cmp_ne_u32_e32 vcc, v3, v1
	s_cbranch_vccnz .Lxb_poll_8
	buffer_wbl2 sc1
	v_mov_b32_e32 v3, 0x7400
	s_waitcnt vmcnt(0)
	global_atomic_add v3, v3, v4, s[74:75] sc0
	v_mul_u32_u24_e32 v1, 8, v0
	s_waitcnt vmcnt(0)
	v_add_u32_e32 v3, 1, v3
	v_cmp_ne_u32_e32 vcc, v3, v1
	s_cbranch_vccnz .Lxb_poll_8
	v_mov_b32_e32 v3, 0x7500
	global_atomic_add v3, v4, s[74:75]
	buffer_inv sc1
	s_branch .Lxb_done_8

.Lxb_loop_8:
	global_load_dword v1, v3, s[74:75] sc1
	s_waitcnt vmcnt(0)
	v_cmp_gt_u32_e32 vcc, 8, v1
	s_cbranch_vccz .Lxb_done_8
	s_sleep 1
	s_add_u32 s3, s3, -1
	s_cmp_lg_u32 s3, 0
	s_cbranch_scc1 .Lxb_loop_8

.LBB0_1241:
	s_waitcnt vmcnt(0)
	s_waitcnt lgkmcnt(0)
	s_barrier
	s_mov_b64 s[0:1], exec
	v_readlane_b32 s4, v238, 1
	v_readlane_b32 s5, v238, 2
	s_and_b64 s[4:5], s[0:1], s[4:5]
	s_mov_b64 exec, s[4:5]
	s_cbranch_execz .LBB0_1293
	s_getreg_b32 s3, hwreg(HW_REG_XCC_ID, 0, 4)
	s_lshl_b32 s3, s3, 8
	s_add_u32 s4, s74, 0x5400
	s_addc_u32 s5, s75, 0
	s_add_u32 s4, s4, s3
	s_addc_u32 s5, s5, 0
	v_mov_b32_e32 v3, 0
	v_mov_b32_e32 v4, 1
	s_waitcnt vmcnt(0) expcnt(0) lgkmcnt(0)
	global_atomic_add v3, v3, v4, s[4:5] sc0
	v_mov_b32_e32 v0, 0x20160
	ds_read_b32 v2, v0
	ds_read_b32 v0, v0 offset:4
	s_waitcnt vmcnt(0) lgkmcnt(0)
	v_mul_u32_u24_e32 v1, 9, v2
	v_add_u32_e32 v3, 1, v3
	v_cmp_ne_u32_e32 vcc, v3, v1
	s_cbranch_vccnz .Lxb_poll_9
	buffer_wbl2 sc1
	v_mov_b32_e32 v3, 0x7400
	s_waitcnt vmcnt(0)
	global_atomic_add v3, v3, v4, s[74:75] sc0
	v_mul_u32_u24_e32 v1, 9, v0
	s_waitcnt vmcnt(0)
	v_add_u32_e32 v3, 1, v3
	v_cmp_ne_u32_e32 vcc, v3, v1
	s_cbranch_vccnz .Lxb_poll_9
	v_mov_b32_e32 v3, 0x7500
	global_atomic_add v3, v4, s[74:75]
	buffer_inv sc1
	s_branch .Lxb_done_9

.Lxb_loop_9:
	global_load_dword v1, v3, s[74:75] sc1
	s_waitcnt vmcnt(0)
	v_cmp_gt_u32_e32 vcc, 9, v1
	s_cbranch_vccz .Lxb_done_9
	s_sleep 1
	s_add_u32 s3, s3, -1
	s_cmp_lg_u32 s3, 0
	s_cbranch_scc1 .Lxb_loop_9

.LBB0_1317:
	s_waitcnt vmcnt(0)
	s_barrier
	s_mov_b64 s[0:1], exec
	v_readlane_b32 s4, v238, 1
	v_readlane_b32 s5, v238, 2
	s_and_b64 s[4:5], s[0:1], s[4:5]
	s_mov_b64 exec, s[4:5]
	s_cbranch_execz .LBB0_1369
	s_getreg_b32 s3, hwreg(HW_REG_XCC_ID, 0, 4)
	s_lshl_b32 s3, s3, 8
	s_add_u32 s4, s74, 0x5400
	s_addc_u32 s5, s75, 0
	s_add_u32 s4, s4, s3
	s_addc_u32 s5, s5, 0
	v_mov_b32_e32 v3, 0
	v_mov_b32_e32 v4, 1
	s_waitcnt vmcnt(0) expcnt(0) lgkmcnt(0)
	global_atomic_add v3, v3, v4, s[4:5] sc0
	v_mov_b32_e32 v0, 0x20160
	ds_read_b32 v2, v0
	ds_read_b32 v0, v0 offset:4
	s_waitcnt vmcnt(0) lgkmcnt(0)
	v_mul_u32_u24_e32 v1, 10, v2
	v_add_u32_e32 v3, 1, v3
	v_cmp_ne_u32_e32 vcc, v3, v1
	s_cbranch_vccnz .Lxb_poll_10
	buffer_wbl2 sc1
	v_mov_b32_e32 v3, 0x7400
	s_waitcnt vmcnt(0)
	global_atomic_add v3, v3, v4, s[74:75] sc0
	v_mul_u32_u24_e32 v1, 10, v0
	s_waitcnt vmcnt(0)
	v_add_u32_e32 v3, 1, v3
	v_cmp_ne_u32_e32 vcc, v3, v1
	s_cbranch_vccnz .Lxb_poll_10
	v_mov_b32_e32 v3, 0x7500
	global_atomic_add v3, v4, s[74:75]
	buffer_inv sc1
	s_branch .Lxb_done_10

.Lxb_loop_10:
	global_load_dword v1, v3, s[74:75] sc1
	s_waitcnt vmcnt(0)
	v_cmp_gt_u32_e32 vcc, 10, v1
	s_cbranch_vccz .Lxb_done_10
	s_sleep 1
	s_add_u32 s3, s3, -1
	s_cmp_lg_u32 s3, 0
	s_cbranch_scc1 .Lxb_loop_10
